# output phase: one static priority raise for the wave half that runs a barrier behind (on top of the VALU-free GEMM K-loops)
# baseline (speedup 1.0000x reference)
; __device__ __forceinline__ void phase_out(const Params& p, unsigned char* shm) {
;     constexpr int LD = 72, TILE = 64 * LD, NPAIR = NCH * 8;
;     const int tid = threadIdx.x, lane = tid & 63, wid = tid >> 6, fr = lane & 15, fq = lane >> 4;
;     const int half = wid >> 2, nt = wid & 3, th = tid & 255, crow = th >> 3, cseg = (th & 7) * 8;
;     bf16_t* base = (bf16_t*)shm + half * 7 * TILE;
;     bf16_t* SbT = base; bf16_t* UTt = base + TILE; bf16_t* Qt = base + 2 * TILE; bf16_t* AQt = base + 3 * TILE; bf16_t* YVt = base + 4 * TILE; bf16_t* PVt = base + 5 * TILE; bf16_t* GBt = base + 6 * TILE;
;     u32x4 g[7][2];
;     auto gload = [&](int pr) {
;         const int item = 2 * pr + half, h = item & 15, row0 = (item >> 4) * 64; const size_t cb = (size_t)item * 4096;
; #pragma unroll
;         for (int i = 0; i < 2; ++i) { const int r = crow + 32 * i; const size_t o = cb + r * 64 + cseg;
;             g[0][i] = *(const u32x4*)(p.Z + (size_t)(row0 + r) * LDZ + ZC_S + h * 64 + cseg);
;             g[1][i] = *(const u32x4*)(p.UTG + o); g[2][i] = *(const u32x4*)(p.QG + o); g[3][i] = *(const u32x4*)(p.AQBG + o); g[4][i] = *(const u32x4*)(p.YVG + o);
;             g[5][i] = *(const u32x4*)(p.PV + ((size_t)(row0 + r) * 16 + h) * 64 + cseg);
;             g[6][i] = *(const u32x4*)(p.Z + (size_t)(row0 + r) * LDZ + ZC_GB + h * 64 + cseg); }
;     };
;     if ((int)blockIdx.x < NPAIR) gload(blockIdx.x);
;     for (int pr = blockIdx.x; pr < NPAIR; pr += gridDim.x) {
;         const int item = 2 * pr + half, h = item & 15, row0 = (item >> 4) * 64;
;         const float rk = p.PRK[(size_t)(row0 + 16 * nt + fr) * 16 + h];
;         f32x4 gng[4], gnb[4];
; #pragma unroll
;         for (int mv = 0; mv < 4; ++mv) { gng[mv] = *(const f32x4*)(p.gn_g + h * 64 + 16 * mv + 4 * fq); gnb[mv] = *(const f32x4*)(p.gn_b + h * 64 + 16 * mv + 4 * fq); }
; #pragma unroll
;         for (int a = 0; a < 7; ++a)
; #pragma unroll
;             for (int i = 0; i < 2; ++i) *(u32x4*)(base + a * TILE + (crow + 32 * i) * LD + cseg) = g[a][i];
;         { const int npr = pr + (int)gridDim.x; gload(npr < NPAIR ? npr : pr); }
.LBB0_496:
	s_or_b64 exec, exec, s[2:3]
	s_cmpk_gt_i32 s40, 0x10ff
	s_barrier
	s_cbranch_scc1 .LBB0_499
	s_load_dwordx2 s[2:3], s[0:1], 0xb8
	v_lshrrev_b32_e32 v109, 8, v133
	v_lshl_add_u32 v104, s40, 1, v109
	s_waitcnt vmcnt(2)
	v_lshlrev_b32_e32 v0, 2, v104
	v_and_b32_e32 v111, 31, v164
	v_and_b32_e32 v26, 0xffffffc0, v0
	v_or_b32_e32 v20, v26, v111
	s_movk_i32 s10, 0x3a00
	s_waitcnt lgkmcnt(0)
	v_mov_b64_e32 v[0:1], s[2:3]
	v_lshlrev_b32_e32 v2, 7, v104
	v_and_b32_e32 v56, 56, v131
	v_mov_b32_e32 v107, 0
	v_mad_i64_i32 v[0:1], s[4:5], v20, s10, v[0:1]
	v_and_b32_e32 v106, 0x780, v2
	v_lshlrev_b32_e32 v58, 1, v56
	v_mov_b32_e32 v59, v107
	v_lshl_add_u64 v[0:1], v[0:1], 0, v[106:107]
	v_lshl_add_u64 v[24:25], v[0:1], 0, v[58:59]
	s_movk_i32 s11, 0x1000
	v_add_co_u32_e32 v0, vcc, s11, v24
	v_ashrrev_i32_e32 v105, 31, v104
	s_nop 0
	v_addc_co_u32_e32 v1, vcc, 0, v25, vcc
	s_movk_i32 s20, 0x3000
	v_lshlrev_b64 v[32:33], 12, v[104:105]
	s_load_dwordx8 s[12:19], s[0:1], 0xe0
	v_add_co_u32_e32 v34, vcc, s20, v24
	v_or_b32_e32 v105, 32, v111
	s_nop 0
	v_addc_co_u32_e32 v35, vcc, 0, v25, vcc
	v_or_b32_e32 v48, v26, v105
	v_mov_b64_e32 v[24:25], s[2:3]
	s_load_dwordx2 s[4:5], s[0:1], 0x100
	s_load_dwordx2 s[6:7], s[0:1], 0x128
	v_mad_i64_i32 v[24:25], s[8:9], v48, s10, v[24:25]
	v_ashrrev_i32_e32 v21, 31, v20
	v_lshl_add_u64 v[24:25], v[24:25], 0, v[106:107]
	v_lshl_or_b32 v108, v111, 6, v56
	v_lshlrev_b64 v[20:21], 11, v[20:21]
	v_ashrrev_i32_e32 v49, 31, v48
	v_lshl_add_u64 v[52:53], v[24:25], 0, v[58:59]
	v_or_b32_e32 v4, v32, v108
	v_mov_b32_e32 v5, v33
	s_waitcnt lgkmcnt(0)
	v_lshl_add_u64 v[20:21], s[12:13], 0, v[20:21]
	v_lshl_or_b32 v110, v105, 6, v56
	v_add_co_u32_e32 v36, vcc, s11, v52
	v_lshlrev_b64 v[48:49], 11, v[48:49]
	v_lshlrev_b64 v[16:17], 1, v[4:5]
	v_lshl_add_u64 v[20:21], v[20:21], 0, v[106:107]
	v_or_b32_e32 v32, v32, v110
	v_addc_co_u32_e32 v37, vcc, 0, v53, vcc
	v_lshl_add_u64 v[48:49], s[12:13], 0, v[48:49]
	v_lshl_add_u64 v[4:5], s[4:5], 0, v[16:17]
	s_waitcnt vmcnt(0)
	v_lshl_add_u64 v[8:9], s[14:15], 0, v[16:17]
	v_lshl_add_u64 v[12:13], s[16:17], 0, v[16:17]
	v_lshl_add_u64 v[16:17], s[18:19], 0, v[16:17]
	v_lshl_add_u64 v[20:21], v[20:21], 0, v[58:59]
	v_lshlrev_b64 v[44:45], 1, v[32:33]
	v_lshl_add_u64 v[48:49], v[48:49], 0, v[106:107]
	v_add_co_u32_e32 v52, vcc, s20, v52
	global_load_dwordx4 v[0:3], v[0:1], off offset:2048
	v_lshl_add_u64 v[32:33], s[4:5], 0, v[44:45]
	global_load_dwordx4 v[4:7], v[4:5], off
	v_lshl_add_u64 v[40:41], s[16:17], 0, v[44:45]
	global_load_dwordx4 v[8:11], v[8:9], off
	v_lshl_add_u64 v[48:49], v[48:49], 0, v[58:59]
	global_load_dwordx4 v[12:15], v[12:13], off
	v_addc_co_u32_e32 v53, vcc, 0, v53, vcc
	global_load_dwordx4 v[16:19], v[16:17], off
	v_lshrrev_b32_e32 v60, 2, v133
	global_load_dwordx4 v[20:23], v[20:21], off
	s_nop 0
	global_load_dwordx4 v[24:27], v[34:35], off offset:256
	global_load_dwordx4 v[28:31], v[36:37], off offset:2048
	v_lshl_add_u64 v[36:37], s[14:15], 0, v[44:45]
	v_lshl_add_u64 v[44:45], s[18:19], 0, v[44:45]
	global_load_dwordx4 v[32:35], v[32:33], off
	s_load_dwordx4 s[24:27], s[0:1], 0x98
	global_load_dwordx4 v[36:39], v[36:37], off
	s_mov_b32 s8, 0xfc00
	global_load_dwordx4 v[40:43], v[40:41], off
	v_bfe_u32 v59, v133, 4, 2
	global_load_dwordx4 v[44:47], v[44:45], off
	v_and_or_b32 v119, v60, 48, v161
	global_load_dwordx4 v[48:51], v[48:49], off
	v_mad_u32_u24 v57, v109, s8, 0
	global_load_dwordx4 v[52:55], v[52:53], off offset:256
	v_mul_u32_u24_e32 v60, 0x90, v119
	v_lshlrev_b32_e32 v122, 3, v59
	v_lshlrev_b32_e32 v106, 4, v59
	v_add_u32_e32 v58, v57, v58
	v_add3_u32 v123, v57, v60, v122
	v_add_u32_e32 v57, v57, v106
	v_mul_u32_u24_e32 v59, 0x90, v111
	v_mul_u32_u24_e32 v60, 0x90, v161
	v_readlane_b32 s8, v244, 3
	s_waitcnt lgkmcnt(0)
	v_lshl_add_u64 v[112:113], s[24:25], 0, v[106:107]
	v_lshl_add_u64 v[114:115], s[26:27], 0, v[106:107]
	v_lshl_add_u32 v124, v109, 2, s8
	s_lshl_b32 s21, s38, 3
	s_lshl_b32 s22, s38, 1
	v_add_u32_e32 v125, v58, v59
	v_lshlrev_b32_e32 v116, 1, v56
	v_add_u32_e32 v126, v57, v60
	v_mov_b32_e32 v127, 0x3a27c5ac
	s_mov_b32 s23, 0x800000
	v_mbcnt_hi_u32_b32 v134, -1, v129
	s_mov_b32 s8, s40
	s_waitcnt vmcnt(0)
	v_readfirstlane_b32 s86, v133
	s_nop 3
	s_lshr_b32 s86, s86, 8
	s_cmp_eq_u32 s86, 0
	s_cbranch_scc1 .Lout_stag0
	s_setprio 1
	s_barrier

; __device__ __forceinline__ unsigned xb_add(unsigned* p, unsigned v) { return __hip_atomic_fetch_add(p, v, __ATOMIC_RELAXED, __HIP_MEMORY_SCOPE_AGENT); }
; __device__ __forceinline__ void xcd_barrier(XcdBarrier& b) {
;     asm volatile("s_waitcnt vmcnt(0)" ::: "memory");
;     __syncthreads();
;     if (threadIdx.x == 0) {
;         unsigned* bar = b.bar;
;         __builtin_amdgcn_s_waitcnt(0);
;         if (b.nloc == 0u) xcd_barrier_complete(bar, b.x, b.nloc, b.nx);
;         const unsigned nloc = b.nloc, nx = b.nx;
;         const unsigned old = xb_add(&bar[XB_XSUB(b.x)], 1u);
;         const unsigned gen = old / nloc;
;         if (old + 1u == (gen + 1u) * nloc) {
.LBB0_499:
	s_setprio 0
	s_waitcnt vmcnt(0)
	s_barrier
	s_mov_b64 s[2:3], exec
	v_readlane_b32 s4, v244, 1
	v_readlane_b32 s5, v244, 2
	s_and_b64 s[4:5], s[2:3], s[4:5]
	s_mov_b64 exec, s[4:5]
	s_cbranch_execz .LBB0_552
	v_cmp_eq_u32_e32 vcc, 0, v130
	s_waitcnt vmcnt(0) expcnt(0) lgkmcnt(0)
	s_and_saveexec_b64 s[4:5], vcc
	s_cbranch_execz .LBB0_515
	v_readlane_b32 s6, v244, 0
	s_mul_i32 s20, s39, s6
	s_add_u32 s6, s36, 0x1000
	s_addc_u32 s7, s37, 0
	s_add_u32 s8, s36, 0x1100
	s_addc_u32 s9, s37, 0
	s_add_u32 s10, s36, 0x1200
	s_addc_u32 s11, s37, 0
	s_add_u32 s12, s36, 0x1300
	s_mul_i32 s20, s20, s38
	s_addc_u32 s13, s37, 0
	s_mov_b32 s21, 1
	v_mov_b32_e32 v16, 0
	s_branch .LBB0_503
